# lnmod<1>: two rows of prefetch in flight per wave (row loop unrolled by two, two raw-row buffers) on top of K-loop peel
# speedup vs baseline: 1.0095x; 1.0028x over previous
; __device__ __forceinline__ unsigned pk2(float lo, float hi) { return pg8::cvt_pk_bf16(lo, hi); }
; template <int MODE>
; __device__ __forceinline__ void lnmod_phase(const float* src, float* dst, float* stats, bf16* H, const bf16* zb, const float* lng, const float* lnb, const float* ada_mod  , int lane, int wave, int G) {
;     ...
; #pragma unroll
;         for (int j = 0; j < 4; ++j) {
;             const int c = 4 * lane + 256 * j;
;             if (MODE != 0) { g[j] = gld<f32x4>(lng + c); bb[j] = gld<f32x4>(lnb + c); }
;             if (MODE != 2) { sh[j] = gld<f32x4>(ada_mod + (size_t)b * NADA + c); sc[j] = gld<f32x4>(ada_mod + (size_t)b * NADA + 1024 + c) + 1.f; }
;         }
;         f32x4 v[4], nx[4];
;         const float* rp = src + (size_t)chunk * 32 * D + 4 * lane;
; #pragma unroll
;         for (int j = 0; j < 4; ++j) { if (MODE != 0) { const v2u w = gld<v2u>(zb + (size_t)chunk * 32 * D + 4 * lane + 256 * j); nx[j] = (f32x4){__builtin_bit_cast(float, w.x << 16), __builtin_bit_cast(float, w.x & 0xffff0000u), __builtin_bit_cast(float, w.y << 16), __builtin_bit_cast(float, w.y & 0xffff0000u)}; } else nx[j] = gld<f32x4>(rp + 256 * j); }
;     ...
;                 for (int j = 0; j < 4; ++j) v[j] = v[j] * rstd * g[j] + bb[j];
;             }
;             if (MODE == 2) {
; #pragma unroll
;                 for (int j = 0; j < 4; ++j) gst<f32x4>(dst + (size_t)r * D + 4 * lane + 256 * j, v[j]);
;             } else {
; #pragma unroll
;                 for (int j = 0; j < 4; ++j) { const f32x4 hv = v[j] * sc[j] + sh[j]; v2u o; o.x = pk2(hv.x, hv.y); o.y = pk2(hv.z, hv.w);
;                     gst<v2u>(H + (size_t)r * D + 4 * lane + 256 * j, o); }
.LBB0_1265:
	s_ashr_i32 s0, s14, 8
	s_mul_hi_i32 s1, s0, 0x9000
	s_mul_i32 s0, s0, 0x9000
	s_add_u32 s0, s2, s0
	s_addc_u32 s1, s3, s1
	v_lshl_add_u64 v[68:69], v[48:49], 2, s[0:1]
	v_add_co_u32_e32 v4, vcc, s47, v68
	global_load_dwordx4 v[8:11], v[54:55], off
	global_load_dwordx4 v[12:15], v[56:57], off
	v_addc_co_u32_e32 v5, vcc, 0, v69, vcc
	global_load_dwordx4 v[0:3], v[68:69], off
	s_mov_b64 s[0:1], 0x1000
	global_load_dwordx4 v[4:7], v[4:5], off
	v_lshl_add_u64 v[70:71], v[68:69], 0, s[0:1]
	s_ashr_i32 s15, s14, 31
	s_lshl_b64 s[0:1], s[14:15], 16
	v_lshl_add_u64 v[86:87], v[50:51], 0, s[0:1]
	s_mov_b64 s[16:17], 0
	s_mov_b32 s18, s20
	s_waitcnt vmcnt(0)
	v_pk_add_f32 v[62:63], v[6:7], 1.0 op_sel_hi:[1,0]
	v_pk_add_f32 v[60:61], v[4:5], 1.0 op_sel_hi:[1,0]
	global_load_dwordx4 v[16:19], v[54:55], off offset:1024
	global_load_dwordx4 v[20:23], v[56:57], off offset:1024
	global_load_dwordx4 v[4:7], v[68:69], off offset:1024
	global_load_dwordx4 v[24:27], v[70:71], off offset:1024
	s_waitcnt vmcnt(0)
	v_pk_add_f32 v[66:67], v[26:27], 1.0 op_sel_hi:[1,0]
	v_pk_add_f32 v[64:65], v[24:25], 1.0 op_sel_hi:[1,0]
	global_load_dwordx4 v[32:35], v[54:55], off offset:2048
	global_load_dwordx4 v[36:39], v[56:57], off offset:2048
	global_load_dwordx4 v[24:27], v[68:69], off offset:2048
	global_load_dwordx4 v[28:31], v[70:71], off offset:2048
	s_waitcnt vmcnt(0)
	v_pk_add_f32 v[74:75], v[30:31], 1.0 op_sel_hi:[1,0]
	v_pk_add_f32 v[72:73], v[28:29], 1.0 op_sel_hi:[1,0]
	global_load_dwordx4 v[40:43], v[54:55], off offset:3072
	global_load_dwordx4 v[44:47], v[56:57], off offset:3072
	global_load_dwordx4 v[28:31], v[68:69], off offset:3072
	s_nop 0
	global_load_dwordx4 v[68:71], v[70:71], off offset:3072
	s_waitcnt vmcnt(0)
	v_pk_add_f32 v[70:71], v[70:71], 1.0 op_sel_hi:[1,0]
	v_add_co_u32_e32 v146, vcc, s76, v58
	s_nop 0
	v_addc_co_u32_e32 v147, vcc, 0, v59, vcc
	global_load_dwordx2 v[138:139], v[146:147], off offset:2048
	global_load_dwordx2 v[140:141], v[146:147], off offset:2560
	global_load_dwordx2 v[142:143], v[146:147], off offset:3072
	global_load_dwordx2 v[144:145], v[146:147], off offset:3584
	global_load_dwordx2 v[78:79], v[86:87], off
	global_load_dwordx2 v[82:83], v[86:87], off offset:512
	global_load_dwordx2 v[88:89], v[86:87], off offset:1024
	v_pk_add_f32 v[68:69], v[68:69], 1.0 op_sel_hi:[1,0]
	s_waitcnt vmcnt(2)
	v_lshlrev_b32_e32 v76, 16, v78
	v_and_b32_e32 v78, 0xffff0000, v78
	s_waitcnt vmcnt(0)
	v_lshlrev_b32_e32 v84, 16, v88
	v_and_b32_e32 v85, 0xffff0000, v88
	v_lshlrev_b32_e32 v94, 16, v89
	v_and_b32_e32 v95, 0xffff0000, v89
	global_load_dwordx2 v[88:89], v[86:87], off offset:1536
	v_lshlrev_b32_e32 v93, 16, v79
	v_and_b32_e32 v79, 0xffff0000, v79
	v_lshlrev_b32_e32 v80, 16, v82
	v_and_b32_e32 v82, 0xffff0000, v82
	v_lshlrev_b32_e32 v91, 16, v83
	v_and_b32_e32 v83, 0xffff0000, v83
	s_waitcnt vmcnt(0)
	v_lshlrev_b32_e32 v86, 16, v88
	v_and_b32_e32 v88, 0xffff0000, v88
	v_lshlrev_b32_e32 v96, 16, v89
	v_and_b32_e32 v98, 0xffff0000, v89
	s_branch .LBB0_1267
.LBB0_1266:
	s_or_b64 exec, exec, s[0:1]
	v_mov_b32_e32 v122, v76
	v_mov_b32_e32 v123, v78
	s_waitcnt vmcnt(12)
	v_lshlrev_b32_e32 v91, 16, v141
	v_mov_b32_e32 v128, v86
	v_mov_b32_e32 v129, v88
	s_waitcnt vmcnt(10)
	v_lshlrev_b32_e32 v86, 16, v144
	v_and_b32_e32 v88, 0xffff0000, v144
	v_lshlrev_b32_e32 v96, 16, v145
	v_and_b32_e32 v98, 0xffff0000, v145
	v_pk_mul_f32 v[100:101], v[100:101], v[90:91] op_sel_hi:[1,0]
	v_pk_mul_f32 v[102:103], v[122:123], v[90:91] op_sel_hi:[1,0]
	v_mov_b32_e32 v124, v80
	v_mov_b32_e32 v125, v82
	v_pk_fma_f32 v[100:101], v[10:11], v[100:101], v[14:15]
	v_pk_fma_f32 v[102:103], v[8:9], v[102:103], v[12:13]
	v_mov_b32_e32 v126, v84
	v_mov_b32_e32 v127, v85
	v_lshlrev_b32_e32 v84, 16, v142
	v_and_b32_e32 v85, 0xffff0000, v142
	v_lshlrev_b32_e32 v94, 16, v143
	v_and_b32_e32 v95, 0xffff0000, v143
	v_pk_mul_f32 v[104:105], v[104:105], v[90:91] op_sel_hi:[1,0]
	v_pk_mul_f32 v[106:107], v[124:125], v[90:91] op_sel_hi:[1,0]
	s_lshl_b64 s[0:1], s[18:19], 11
	v_pk_fma_f32 v[100:101], v[62:63], v[100:101], v[2:3]
	v_pk_fma_f32 v[102:103], v[60:61], v[102:103], v[0:1]
	v_pk_fma_f32 v[104:105], v[18:19], v[104:105], v[22:23]
	v_pk_fma_f32 v[106:107], v[16:17], v[106:107], v[20:21]
	v_lshl_add_u64 v[122:123], v[52:53], 0, s[0:1]
	v_cvt_pk_bf16_f32 v102, v102, v103
	v_cvt_pk_bf16_f32 v103, v100, v101
	v_lshlrev_b32_e32 v80, 16, v140
	v_and_b32_e32 v83, 0xffff0000, v141
	v_and_b32_e32 v82, 0xffff0000, v140
	v_pk_mul_f32 v[108:109], v[110:111], v[90:91] op_sel_hi:[1,0]
	v_pk_mul_f32 v[110:111], v[126:127], v[90:91] op_sel_hi:[1,0]
	global_store_dwordx2 v[122:123], v[102:103], off
	v_pk_fma_f32 v[100:101], v[66:67], v[104:105], v[6:7]
	v_pk_fma_f32 v[102:103], v[64:65], v[106:107], v[4:5]
	v_pk_fma_f32 v[108:109], v[34:35], v[108:109], v[38:39]
	v_pk_fma_f32 v[110:111], v[32:33], v[110:111], v[36:37]
	v_cvt_pk_bf16_f32 v102, v102, v103
	v_cvt_pk_bf16_f32 v103, v100, v101
	v_lshlrev_b32_e32 v93, 16, v139
	v_lshlrev_b32_e32 v76, 16, v138
	v_and_b32_e32 v79, 0xffff0000, v139
	v_and_b32_e32 v78, 0xffff0000, v138
	v_pk_mul_f32 v[112:113], v[114:115], v[90:91] op_sel_hi:[1,0]
	v_pk_mul_f32 v[114:115], v[128:129], v[90:91] op_sel_hi:[1,0]
	global_store_dwordx2 v[122:123], v[102:103], off offset:512
	v_pk_fma_f32 v[100:101], v[74:75], v[108:109], v[26:27]
	v_pk_fma_f32 v[102:103], v[72:73], v[110:111], v[24:25]
	v_pk_fma_f32 v[112:113], v[42:43], v[112:113], v[46:47]
	v_pk_fma_f32 v[114:115], v[40:41], v[114:115], v[44:45]
	v_cvt_pk_bf16_f32 v102, v102, v103
	v_cvt_pk_bf16_f32 v103, v100, v101
	s_add_u32 s16, s16, 0x800
	global_store_dwordx2 v[122:123], v[102:103], off offset:1024
	v_pk_fma_f32 v[100:101], v[70:71], v[112:113], v[30:31]
	v_pk_fma_f32 v[102:103], v[68:69], v[114:115], v[28:29]
	s_addc_u32 s17, s17, 0
	s_add_i32 s18, s18, 1
	v_cvt_pk_bf16_f32 v102, v102, v103
	v_cvt_pk_bf16_f32 v103, v100, v101
	s_cmpk_eq_u32 s16, 0xf800
	global_store_dwordx2 v[122:123], v[102:103], off offset:1536
	s_cbranch_scc1 .LBB0_1269
; template <int MODE>
; __device__ __forceinline__ void lnmod_phase(const float* src, float* dst, float* stats, bf16* H, const bf16* zb, const float* lng, const float* lnb, const float* ada_mod  , int lane, int wave, int G) {
;     ...
;             if (i + 1 < 32) {
; #pragma unroll
;                 for (int j = 0; j < 4; ++j) { if (MODE != 0) { const v2u w = gld<v2u>(zb + ((size_t)chunk * 32 + i + 1) * D + 4 * lane + 256 * j); nx[j] = (f32x4){__builtin_bit_cast(float, w.x << 16), __builtin_bit_cast(float, w.x & 0xffff0000u), __builtin_bit_cast(float, w.y << 16), __builtin_bit_cast(float, w.y & 0xffff0000u)}; } else nx[j] = gld<f32x4>(rp + (size_t)(i + 1) * D + 256 * j); }
;             }
;             if (MODE != 0) {
;                 float s = 0.f;
; #pragma unroll
;                 for (int j = 0; j < 4; ++j) s += (v[j].x + v[j].y) + (v[j].z + v[j].w);
;                 const float mean = wave_sum(s) * (1.f / D); float s2 = 0.f;
; #pragma unroll
;                 for (int j = 0; j < 4; ++j) { v[j] = v[j] - mean; s2 += (v[j].x * v[j].x + v[j].y * v[j].y) + (v[j].z * v[j].z + v[j].w * v[j].w); }
;                 const float rstd = 1.f / sqrtf(wave_sum(s2) * (1.f / D) + LN_EPS);
;                 if (MODE == 1 && lane == 0) gst<f32x2v>(stats + 2 * (size_t)r, (f32x2v){mean, rstd});
.Lln1_Bh:
	v_mov_b32_e32 v92, v78
	v_mov_b32_e32 v77, v79
	v_pk_add_f32 v[100:101], v[92:93], v[76:77]
	v_mov_b32_e32 v90, v82
	v_mov_b32_e32 v81, v83
	v_add_f32_e32 v77, v100, v101
	v_pk_add_f32 v[100:101], v[90:91], v[80:81]
	v_add_f32_e32 v99, 0, v77
	v_pk_add_f32 v[100:101], v[100:101], v[100:101] op_sel_hi:[0,1]
	v_add_f32_e32 v87, v84, v85
	v_add_f32_e32 v89, v94, v95
	v_mov_b32_e32 v97, v101
	v_pk_add_f32 v[102:103], v[86:87], v[88:89]
	v_pk_add_f32 v[100:101], v[96:97], v[98:99]
	v_mov_b32_e32 v105, v83
	v_pk_add_f32 v[100:101], v[102:103], v[100:101]
	s_add_u32 s24, s16, 0x800
	s_min_u32 s24, s24, 0xf000
	s_mov_b32 s25, 0
	v_lshl_add_u64 v[102:103], v[58:59], 0, s[24:25]
	v_add_f32_e32 v77, v100, v101
	v_mov_b32_e32 v101, v79
	v_add_co_u32_e32 v92, vcc, s76, v102
	v_mov_b32_e32 v100, v93
	s_nop 1
	v_add_f32_dpp v77, v77, v77 quad_perm:[1,0,3,2] row_mask:0xf bank_mask:0xf
	v_addc_co_u32_e32 v93, vcc, 0, v103, vcc
	global_load_dwordx2 v[138:139], v[92:93], off offset:2048
	global_load_dwordx2 v[140:141], v[92:93], off offset:2560
	global_load_dwordx2 v[142:143], v[92:93], off offset:3072
	global_load_dwordx2 v[144:145], v[92:93], off offset:3584
	v_mov_b32_e32 v104, v91
	s_nop 1
	v_add_f32_dpp v77, v77, v77 quad_perm:[2,3,0,1] row_mask:0xf bank_mask:0xf
	v_mov_b32_e32 v111, v95
	v_mov_b32_e32 v110, v94
	v_mov_b32_e32 v115, v98
	v_mov_b32_e32 v114, v96
	s_nop 1
	v_mov_b32_dpp v81, v77 row_half_mirror row_mask:0xf bank_mask:0xf
	s_nop 1
	v_add_f32_dpp v77, v81, v77 quad_perm:[3,2,1,0] row_mask:0xf bank_mask:0xf
	s_ashr_i32 s19, s18, 31
	s_nop 1
	v_mov_b32_dpp v81, v77 row_mirror row_mask:0xf bank_mask:0xf
	s_nop 1
	v_add_f32_dpp v77, v81, v77 row_half_mirror row_mask:0xf bank_mask:0xf
	v_mov_b32_e32 v79, v77
	s_nop 1
	v_permlane16_swap_b32_e32 v79, v77
	v_add_f32_e32 v77, v79, v77
	v_mov_b32_e32 v79, v77
	s_nop 1
	v_permlane32_swap_b32_e32 v79, v77
	v_add_f32_e32 v77, v79, v77
	v_fmac_f32_e32 v101, 0xba800000, v77
	v_fmac_f32_e32 v78, 0xba800000, v77
	v_fmac_f32_e32 v100, 0xba800000, v77
	v_fmac_f32_e32 v76, 0xba800000, v77
	v_mul_f32_e32 v79, v78, v78
	v_mul_f32_e32 v81, v101, v101
	v_fmac_f32_e32 v79, v76, v76
	v_fmac_f32_e32 v81, v100, v100
	v_fmac_f32_e32 v105, 0xba800000, v77
	v_fmac_f32_e32 v82, 0xba800000, v77
	v_add_f32_e32 v79, v79, v81
	v_fmac_f32_e32 v104, 0xba800000, v77
	v_fmac_f32_e32 v80, 0xba800000, v77
	v_mul_f32_e32 v81, v82, v82
	v_mul_f32_e32 v83, v105, v105
	v_fmac_f32_e32 v81, v80, v80
	v_fmac_f32_e32 v83, v104, v104
	v_add_f32_e32 v81, v81, v83
	v_fmac_f32_e32 v111, 0xba800000, v77
	v_fmac_f32_e32 v85, 0xba800000, v77
	v_add_f32_e32 v79, v79, v81
	v_fmac_f32_e32 v110, 0xba800000, v77
	v_fmac_f32_e32 v84, 0xba800000, v77
	v_mul_f32_e32 v81, v85, v85
	v_mul_f32_e32 v83, v111, v111
	v_fmac_f32_e32 v81, v84, v84
	v_fmac_f32_e32 v83, v110, v110
	v_add_f32_e32 v81, v81, v83
	v_fmac_f32_e32 v115, 0xba800000, v77
	v_fmac_f32_e32 v88, 0xba800000, v77
	v_add_f32_e32 v79, v81, v79
	v_fmac_f32_e32 v114, 0xba800000, v77
	v_fmac_f32_e32 v86, 0xba800000, v77
	v_mul_f32_e32 v81, v88, v88
	v_mul_f32_e32 v83, v115, v115
	v_fmac_f32_e32 v81, v86, v86
	v_fmac_f32_e32 v83, v114, v114
	v_add_f32_e32 v81, v81, v83
	v_add_f32_e32 v79, v81, v79
	s_nop 1
	v_add_f32_dpp v79, v79, v79 quad_perm:[1,0,3,2] row_mask:0xf bank_mask:0xf
	s_nop 1
	v_add_f32_dpp v79, v79, v79 quad_perm:[2,3,0,1] row_mask:0xf bank_mask:0xf
	s_nop 1
	v_mov_b32_dpp v81, v79 row_half_mirror row_mask:0xf bank_mask:0xf
	s_nop 1
	v_add_f32_dpp v79, v81, v79 quad_perm:[3,2,1,0] row_mask:0xf bank_mask:0xf
	s_nop 1
	v_mov_b32_dpp v81, v79 row_mirror row_mask:0xf bank_mask:0xf
	s_nop 1
	v_add_f32_dpp v79, v81, v79 row_half_mirror row_mask:0xf bank_mask:0xf
	v_mov_b32_e32 v81, v79
	s_nop 1
	v_permlane16_swap_b32_e32 v81, v79
	v_add_f32_e32 v79, v81, v79
	v_mov_b32_e32 v81, v79
	s_nop 1
	v_permlane32_swap_b32_e32 v81, v79
	v_add_f32_e32 v79, v81, v79
	v_fmamk_f32 v79, v79, 0x3a800000, v205
	v_mul_f32_e32 v81, 0x4f800000, v79
	v_cmp_gt_f32_e32 vcc, s34, v79
	s_nop 1
	v_cndmask_b32_e32 v79, v79, v81, vcc
	v_sqrt_f32_e32 v81, v79
	s_nop 0
	v_add_u32_e32 v83, -1, v81
	v_fma_f32 v87, -v83, v81, v79
	v_cmp_ge_f32_e64 s[0:1], 0, v87
	v_add_u32_e32 v87, 1, v81
	s_nop 0
	v_cndmask_b32_e64 v83, v81, v83, s[0:1]
	v_fma_f32 v81, -v87, v81, v79
	v_cmp_lt_f32_e64 s[0:1], 0, v81
	s_nop 1
	v_cndmask_b32_e64 v81, v83, v87, s[0:1]
	v_mul_f32_e32 v83, 0x37800000, v81
	v_cndmask_b32_e32 v81, v81, v83, vcc
	v_cmp_class_f32_e32 vcc, v79, v204
	s_nop 1
	v_cndmask_b32_e32 v79, v81, v79, vcc
	v_div_scale_f32 v81, s[0:1], v79, v79, 1.0
	v_rcp_f32_e32 v83, v81
	s_nop 0
	v_fma_f32 v87, -v81, v83, 1.0
	v_fmac_f32_e32 v83, v87, v83
	v_div_scale_f32 v87, vcc, 1.0, v79, 1.0
	v_mul_f32_e32 v89, v87, v83
	v_fma_f32 v90, -v81, v89, v87
	v_fmac_f32_e32 v89, v90, v83
	v_fma_f32 v81, -v81, v89, v87
	v_div_fmas_f32 v81, v81, v83, v89
	v_div_fixup_f32 v90, v81, v79, 1.0
	s_and_saveexec_b64 s[0:1], s[4:5]
	s_cbranch_execz .Lln1_Bt
	s_lshl_b64 s[42:43], s[18:19], 3
	s_add_u32 s42, s74, s42
	v_mul_f32_e32 v92, 0x3a800000, v77
	s_addc_u32 s43, s75, s43
	v_mov_b32_e32 v93, v90
	global_store_dwordx2 v165, v[92:93], s[42:43]
; __device__ __forceinline__ unsigned pk2(float lo, float hi) { return pg8::cvt_pk_bf16(lo, hi); }
; template <int MODE>
; __device__ __forceinline__ void lnmod_phase(const float* src, float* dst, float* stats, bf16* H, const bf16* zb, const float* lng, const float* lnb, const float* ada_mod  , int lane, int wave, int G) {
;     ...
;                 for (int j = 0; j < 4; ++j) { if (MODE != 0) { const v2u w = gld<v2u>(zb + ((size_t)chunk * 32 + i + 1) * D + 4 * lane + 256 * j); nx[j] = (f32x4){__builtin_bit_cast(float, w.x << 16), __builtin_bit_cast(float, w.x & 0xffff0000u), __builtin_bit_cast(float, w.y << 16), __builtin_bit_cast(float, w.y & 0xffff0000u)}; } else nx[j] = gld<f32x4>(rp + (size_t)(i + 1) * D + 256 * j); }
;             }
;             if (MODE != 0) {
;                 float s = 0.f;
; #pragma unroll
;                 for (int j = 0; j < 4; ++j) s += (v[j].x + v[j].y) + (v[j].z + v[j].w);
;                 const float mean = wave_sum(s) * (1.f / D); float s2 = 0.f;
; #pragma unroll
;                 for (int j = 0; j < 4; ++j) { v[j] = v[j] - mean; s2 += (v[j].x * v[j].x + v[j].y * v[j].y) + (v[j].z * v[j].z + v[j].w * v[j].w); }
;                 const float rstd = 1.f / sqrtf(wave_sum(s2) * (1.f / D) + LN_EPS);
;                 if (MODE == 1 && lane == 0) gst<f32x2v>(stats + 2 * (size_t)r, (f32x2v){mean, rstd});
; #pragma unroll
;                 for (int j = 0; j < 4; ++j) v[j] = v[j] * rstd * g[j] + bb[j];
;             }
;             if (MODE == 2) {
; #pragma unroll
;                 for (int j = 0; j < 4; ++j) gst<f32x4>(dst + (size_t)r * D + 4 * lane + 256 * j, v[j]);
;             } else {
; #pragma unroll
;                 for (int j = 0; j < 4; ++j) { const f32x4 hv = v[j] * sc[j] + sh[j]; v2u o; o.x = pk2(hv.x, hv.y); o.y = pk2(hv.z, hv.w);
;                     gst<v2u>(H + (size_t)r * D + 4 * lane + 256 * j, o); }
.Lln1_Bt:
	s_or_b64 exec, exec, s[0:1]
	v_mov_b32_e32 v122, v76
	v_mov_b32_e32 v123, v78
	s_waitcnt vmcnt(12)
	v_lshlrev_b32_e32 v91, 16, v133
	v_mov_b32_e32 v128, v86
	v_mov_b32_e32 v129, v88
	s_waitcnt vmcnt(10)
	v_lshlrev_b32_e32 v86, 16, v136
	v_and_b32_e32 v88, 0xffff0000, v136
	v_lshlrev_b32_e32 v96, 16, v137
	v_and_b32_e32 v98, 0xffff0000, v137
	v_pk_mul_f32 v[100:101], v[100:101], v[90:91] op_sel_hi:[1,0]
	v_pk_mul_f32 v[102:103], v[122:123], v[90:91] op_sel_hi:[1,0]
	v_mov_b32_e32 v124, v80
	v_mov_b32_e32 v125, v82
	v_pk_fma_f32 v[100:101], v[10:11], v[100:101], v[14:15]
	v_pk_fma_f32 v[102:103], v[8:9], v[102:103], v[12:13]
	v_mov_b32_e32 v126, v84
	v_mov_b32_e32 v127, v85
	v_lshlrev_b32_e32 v84, 16, v134
	v_and_b32_e32 v85, 0xffff0000, v134
	v_lshlrev_b32_e32 v94, 16, v135
	v_and_b32_e32 v95, 0xffff0000, v135
	v_pk_mul_f32 v[104:105], v[104:105], v[90:91] op_sel_hi:[1,0]
	v_pk_mul_f32 v[106:107], v[124:125], v[90:91] op_sel_hi:[1,0]
	s_lshl_b64 s[0:1], s[18:19], 11
	v_pk_fma_f32 v[100:101], v[62:63], v[100:101], v[2:3]
	v_pk_fma_f32 v[102:103], v[60:61], v[102:103], v[0:1]
	v_pk_fma_f32 v[104:105], v[18:19], v[104:105], v[22:23]
	v_pk_fma_f32 v[106:107], v[16:17], v[106:107], v[20:21]
	v_lshl_add_u64 v[122:123], v[52:53], 0, s[0:1]
	v_cvt_pk_bf16_f32 v102, v102, v103
	v_cvt_pk_bf16_f32 v103, v100, v101
	v_lshlrev_b32_e32 v80, 16, v132
	v_and_b32_e32 v83, 0xffff0000, v133
	v_and_b32_e32 v82, 0xffff0000, v132
	v_pk_mul_f32 v[108:109], v[110:111], v[90:91] op_sel_hi:[1,0]
	v_pk_mul_f32 v[110:111], v[126:127], v[90:91] op_sel_hi:[1,0]
	global_store_dwordx2 v[122:123], v[102:103], off
	v_pk_fma_f32 v[100:101], v[66:67], v[104:105], v[6:7]
	v_pk_fma_f32 v[102:103], v[64:65], v[106:107], v[4:5]
	v_pk_fma_f32 v[108:109], v[34:35], v[108:109], v[38:39]
	v_pk_fma_f32 v[110:111], v[32:33], v[110:111], v[36:37]
	v_cvt_pk_bf16_f32 v102, v102, v103
	v_cvt_pk_bf16_f32 v103, v100, v101
	v_lshlrev_b32_e32 v93, 16, v131
	v_lshlrev_b32_e32 v76, 16, v130
	v_and_b32_e32 v79, 0xffff0000, v131
	v_and_b32_e32 v78, 0xffff0000, v130
	v_pk_mul_f32 v[112:113], v[114:115], v[90:91] op_sel_hi:[1,0]
	v_pk_mul_f32 v[114:115], v[128:129], v[90:91] op_sel_hi:[1,0]
	global_store_dwordx2 v[122:123], v[102:103], off offset:512
	v_pk_fma_f32 v[100:101], v[74:75], v[108:109], v[26:27]
	v_pk_fma_f32 v[102:103], v[72:73], v[110:111], v[24:25]
	v_pk_fma_f32 v[112:113], v[42:43], v[112:113], v[46:47]
	v_pk_fma_f32 v[114:115], v[40:41], v[114:115], v[44:45]
	v_cvt_pk_bf16_f32 v102, v102, v103
	v_cvt_pk_bf16_f32 v103, v100, v101
	s_add_u32 s16, s16, 0x800
	global_store_dwordx2 v[122:123], v[102:103], off offset:1024
	v_pk_fma_f32 v[100:101], v[70:71], v[112:113], v[30:31]
	v_pk_fma_f32 v[102:103], v[68:69], v[114:115], v[28:29]
	s_addc_u32 s17, s17, 0
	s_add_i32 s18, s18, 1
	v_cvt_pk_bf16_f32 v102, v102, v103
	v_cvt_pk_bf16_f32 v103, v100, v101
	s_cmpk_eq_u32 s16, 0xf800
	global_store_dwordx2 v[122:123], v[102:103], off offset:1536
	s_cbranch_scc1 .LBB0_1269
; template <int MODE>
; __device__ __forceinline__ void lnmod_phase(const float* src, float* dst, float* stats, bf16* H, const bf16* zb, const float* lng, const float* lnb, const float* ada_mod  , int lane, int wave, int G) {
;     ...
;             if (i + 1 < 32) {
; #pragma unroll
;                 for (int j = 0; j < 4; ++j) { if (MODE != 0) { const v2u w = gld<v2u>(zb + ((size_t)chunk * 32 + i + 1) * D + 4 * lane + 256 * j); nx[j] = (f32x4){__builtin_bit_cast(float, w.x << 16), __builtin_bit_cast(float, w.x & 0xffff0000u), __builtin_bit_cast(float, w.y << 16), __builtin_bit_cast(float, w.y & 0xffff0000u)}; } else nx[j] = gld<f32x4>(rp + (size_t)(i + 1) * D + 256 * j); }
;             }
;             if (MODE != 0) {
;                 float s = 0.f;
; #pragma unroll
;                 for (int j = 0; j < 4; ++j) s += (v[j].x + v[j].y) + (v[j].z + v[j].w);
;                 const float mean = wave_sum(s) * (1.f / D); float s2 = 0.f;
; #pragma unroll
;                 for (int j = 0; j < 4; ++j) { v[j] = v[j] - mean; s2 += (v[j].x * v[j].x + v[j].y * v[j].y) + (v[j].z * v[j].z + v[j].w * v[j].w); }
;                 const float rstd = 1.f / sqrtf(wave_sum(s2) * (1.f / D) + LN_EPS);
;                 if (MODE == 1 && lane == 0) gst<f32x2v>(stats + 2 * (size_t)r, (f32x2v){mean, rstd});
.LBB0_1267:
	v_mov_b32_e32 v92, v78
	v_mov_b32_e32 v77, v79
	v_pk_add_f32 v[100:101], v[92:93], v[76:77]
	v_mov_b32_e32 v90, v82
	v_mov_b32_e32 v81, v83
	v_add_f32_e32 v77, v100, v101
	v_pk_add_f32 v[100:101], v[90:91], v[80:81]
	v_add_f32_e32 v99, 0, v77
	v_pk_add_f32 v[100:101], v[100:101], v[100:101] op_sel_hi:[0,1]
	v_add_f32_e32 v87, v84, v85
	v_add_f32_e32 v89, v94, v95
	v_mov_b32_e32 v97, v101
	v_pk_add_f32 v[102:103], v[86:87], v[88:89]
	v_pk_add_f32 v[100:101], v[96:97], v[98:99]
	v_mov_b32_e32 v105, v83
	v_pk_add_f32 v[100:101], v[102:103], v[100:101]
	s_add_u32 s24, s16, 0x800
	s_min_u32 s24, s24, 0xf000
	s_mov_b32 s25, 0
	v_lshl_add_u64 v[102:103], v[58:59], 0, s[24:25]
	v_add_f32_e32 v77, v100, v101
	v_mov_b32_e32 v101, v79
	v_add_co_u32_e32 v92, vcc, s76, v102
	v_mov_b32_e32 v100, v93
	s_nop 1
	v_add_f32_dpp v77, v77, v77 quad_perm:[1,0,3,2] row_mask:0xf bank_mask:0xf
	v_addc_co_u32_e32 v93, vcc, 0, v103, vcc
	global_load_dwordx2 v[130:131], v[92:93], off offset:2048
	global_load_dwordx2 v[132:133], v[92:93], off offset:2560
	global_load_dwordx2 v[134:135], v[92:93], off offset:3072
	global_load_dwordx2 v[136:137], v[92:93], off offset:3584
	v_mov_b32_e32 v104, v91
	s_nop 1
	v_add_f32_dpp v77, v77, v77 quad_perm:[2,3,0,1] row_mask:0xf bank_mask:0xf
	v_mov_b32_e32 v111, v95
	v_mov_b32_e32 v110, v94
	v_mov_b32_e32 v115, v98
	v_mov_b32_e32 v114, v96
	s_nop 1
	v_mov_b32_dpp v81, v77 row_half_mirror row_mask:0xf bank_mask:0xf
	s_nop 1
	v_add_f32_dpp v77, v81, v77 quad_perm:[3,2,1,0] row_mask:0xf bank_mask:0xf
	s_ashr_i32 s19, s18, 31
	s_nop 1
	v_mov_b32_dpp v81, v77 row_mirror row_mask:0xf bank_mask:0xf
	s_nop 1
	v_add_f32_dpp v77, v81, v77 row_half_mirror row_mask:0xf bank_mask:0xf
	v_mov_b32_e32 v79, v77
	s_nop 1
	v_permlane16_swap_b32_e32 v79, v77
	v_add_f32_e32 v77, v79, v77
	v_mov_b32_e32 v79, v77
	s_nop 1
	v_permlane32_swap_b32_e32 v79, v77
	v_add_f32_e32 v77, v79, v77
	v_fmac_f32_e32 v101, 0xba800000, v77
	v_fmac_f32_e32 v78, 0xba800000, v77
	v_fmac_f32_e32 v100, 0xba800000, v77
	v_fmac_f32_e32 v76, 0xba800000, v77
	v_mul_f32_e32 v79, v78, v78
	v_mul_f32_e32 v81, v101, v101
	v_fmac_f32_e32 v79, v76, v76
	v_fmac_f32_e32 v81, v100, v100
	v_fmac_f32_e32 v105, 0xba800000, v77
	v_fmac_f32_e32 v82, 0xba800000, v77
	v_add_f32_e32 v79, v79, v81
	v_fmac_f32_e32 v104, 0xba800000, v77
	v_fmac_f32_e32 v80, 0xba800000, v77
	v_mul_f32_e32 v81, v82, v82
	v_mul_f32_e32 v83, v105, v105
	v_fmac_f32_e32 v81, v80, v80
	v_fmac_f32_e32 v83, v104, v104
	v_add_f32_e32 v81, v81, v83
	v_fmac_f32_e32 v111, 0xba800000, v77
	v_fmac_f32_e32 v85, 0xba800000, v77
	v_add_f32_e32 v79, v79, v81
	v_fmac_f32_e32 v110, 0xba800000, v77
	v_fmac_f32_e32 v84, 0xba800000, v77
	v_mul_f32_e32 v81, v85, v85
	v_mul_f32_e32 v83, v111, v111
	v_fmac_f32_e32 v81, v84, v84
	v_fmac_f32_e32 v83, v110, v110
	v_add_f32_e32 v81, v81, v83
	v_fmac_f32_e32 v115, 0xba800000, v77
	v_fmac_f32_e32 v88, 0xba800000, v77
	v_add_f32_e32 v79, v81, v79
	v_fmac_f32_e32 v114, 0xba800000, v77
	v_fmac_f32_e32 v86, 0xba800000, v77
	v_mul_f32_e32 v81, v88, v88
	v_mul_f32_e32 v83, v115, v115
	v_fmac_f32_e32 v81, v86, v86
	v_fmac_f32_e32 v83, v114, v114
	v_add_f32_e32 v81, v81, v83
	v_add_f32_e32 v79, v81, v79
	s_nop 1
	v_add_f32_dpp v79, v79, v79 quad_perm:[1,0,3,2] row_mask:0xf bank_mask:0xf
	s_nop 1
	v_add_f32_dpp v79, v79, v79 quad_perm:[2,3,0,1] row_mask:0xf bank_mask:0xf
	s_nop 1
	v_mov_b32_dpp v81, v79 row_half_mirror row_mask:0xf bank_mask:0xf
	s_nop 1
	v_add_f32_dpp v79, v81, v79 quad_perm:[3,2,1,0] row_mask:0xf bank_mask:0xf
	s_nop 1
	v_mov_b32_dpp v81, v79 row_mirror row_mask:0xf bank_mask:0xf
	s_nop 1
	v_add_f32_dpp v79, v81, v79 row_half_mirror row_mask:0xf bank_mask:0xf
	v_mov_b32_e32 v81, v79
	s_nop 1
	v_permlane16_swap_b32_e32 v81, v79
	v_add_f32_e32 v79, v81, v79
	v_mov_b32_e32 v81, v79
	s_nop 1
	v_permlane32_swap_b32_e32 v81, v79
	v_add_f32_e32 v79, v81, v79
	v_fmamk_f32 v79, v79, 0x3a800000, v205
	v_mul_f32_e32 v81, 0x4f800000, v79
	v_cmp_gt_f32_e32 vcc, s34, v79
	s_nop 1
	v_cndmask_b32_e32 v79, v79, v81, vcc
	v_sqrt_f32_e32 v81, v79
	s_nop 0
	v_add_u32_e32 v83, -1, v81
	v_fma_f32 v87, -v83, v81, v79
	v_cmp_ge_f32_e64 s[0:1], 0, v87
	v_add_u32_e32 v87, 1, v81
	s_nop 0
	v_cndmask_b32_e64 v83, v81, v83, s[0:1]
	v_fma_f32 v81, -v87, v81, v79
	v_cmp_lt_f32_e64 s[0:1], 0, v81
	s_nop 1
	v_cndmask_b32_e64 v81, v83, v87, s[0:1]
	v_mul_f32_e32 v83, 0x37800000, v81
	v_cndmask_b32_e32 v81, v81, v83, vcc
	v_cmp_class_f32_e32 vcc, v79, v204
	s_nop 1
	v_cndmask_b32_e32 v79, v81, v79, vcc
	v_div_scale_f32 v81, s[0:1], v79, v79, 1.0
	v_rcp_f32_e32 v83, v81
	s_nop 0
	v_fma_f32 v87, -v81, v83, 1.0
	v_fmac_f32_e32 v83, v87, v83
	v_div_scale_f32 v87, vcc, 1.0, v79, 1.0
	v_mul_f32_e32 v89, v87, v83
	v_fma_f32 v90, -v81, v89, v87
	v_fmac_f32_e32 v89, v90, v83
	v_fma_f32 v81, -v81, v89, v87
	v_div_fmas_f32 v81, v81, v83, v89
	v_div_fixup_f32 v90, v81, v79, 1.0
	s_and_saveexec_b64 s[0:1], s[4:5]
	s_cbranch_execz .LBB0_1266
	s_lshl_b64 s[42:43], s[18:19], 3
	s_add_u32 s42, s74, s42
	v_mul_f32_e32 v92, 0x3a800000, v77
	s_addc_u32 s43, s75, s43
	v_mov_b32_e32 v93, v90
	global_store_dwordx2 v165, v[92:93], s[42:43]
	s_branch .LBB0_1266
